# v35 + next-chunk prefetch with scalar-base addressing, loads spread through step 2
# speedup vs baseline: 1.0394x; 1.0118x over previous
.LBB0_380:
	s_or_b64 exec, exec, s[94:95]
	s_add_i32 s14, s15, 1
	s_cmp_lt_u32 s14, s0
	s_cselect_b32 s15, s14, s15
	s_lshl_b32 s16, s15, 6
	v_add_u32_e32 v2, s13, v231
	s_add_i32 s16, s16, s97
	v_ashrrev_i32_e32 v3, 31, v2
	s_cmp_eq_u32 s15, 0
	v_lshlrev_b64 v[2:3], 12, v[2:3]
	s_cselect_b32 s15, 0, 0x1000
	v_lshl_add_u64 v[190:191], v[164:165], 0, v[2:3]
	global_load_dwordx4 v[76:79], v[190:191], off
	global_load_dwordx4 v[80:83], v[190:191], off offset:128
	global_load_dwordx4 v[72:75], v[190:191], off offset:256
	global_load_dwordx4 v[68:71], v[190:191], off offset:384
	s_waitcnt lgkmcnt(0)
	s_barrier
	v_readlane_b32 s98, v254, 52
	v_readlane_b32 s99, v254, 53
	v_readfirstlane_b32 s100, v1
	s_nop 3
	v_subrev_u32_e32 v151, s98, v176
	s_cmp_lg_u32 s100, 0
	s_cselect_b32 s101, 0x1000, s15
	s_add_i32 s100, s100, s16
	s_lshl_b32 s100, s100, 13
	s_add_u32 s98, s98, s100
	s_addc_u32 s99, s99, 0
	s_mul_i32 s100, s101, 6
	s_sub_u32 s98, s98, s100
	s_subb_u32 s99, s99, 0
	s_lshl_b32 s100, s101, 1
	v_add_u32_e32 v2, s16, v159
	v_ashrrev_i32_e32 v3, 31, v2
	v_lshlrev_b64 v[2:3], 7, v[2:3]
	v_lshl_add_u64 v[2:3], s[90:91], 0, v[2:3]
	global_load_dword v153, v[2:3], off
	ds_read_b128 v[84:87], v180
	ds_read_b128 v[88:91], v181 offset:17408
	ds_read_b128 v[92:95], v181 offset:21760
	global_load_dword v250, v151, s[98:99]
	ds_read_b128 v[104:107], v180 offset:64
	ds_read_b128 v[96:99], v181 offset:17472
	ds_read_b128 v[100:103], v181 offset:21824
	ds_read_b128 v[108:111], v180 offset:128
	ds_read_b128 v[112:115], v181 offset:17536
	v_add_u32_e32 v192, v178, v228
	ds_read_b128 v[116:119], v181 offset:21888
	ds_read_b128 v[120:123], v180 offset:192
	s_waitcnt lgkmcnt(8)
	v_mfma_f32_16x16x32_bf16 v[88:91], v[84:87], v[88:91], 0
	s_add_u32 s98, s98, s100
	s_addc_u32 s99, s99, 0
	global_load_dword v251, v151, s[98:99]
	ds_read_b128 v[124:127], v181 offset:17600
	s_waitcnt lgkmcnt(8)
	v_mfma_f32_16x16x32_bf16 v[84:87], v[84:87], v[92:95], 0
	ds_read_b128 v[128:131], v181 offset:21952
	s_waitcnt lgkmcnt(7)
	v_mfma_f32_16x16x32_bf16 v[88:91], v[104:107], v[96:99], v[88:91]
	s_waitcnt lgkmcnt(6)
	v_mfma_f32_16x16x32_bf16 v[84:87], v[104:107], v[100:103], v[84:87]
	s_waitcnt lgkmcnt(4)
	v_mfma_f32_16x16x32_bf16 v[88:91], v[108:111], v[112:115], v[88:91]
	s_add_u32 s98, s98, s100
	s_addc_u32 s99, s99, 0
	global_load_dword v252, v151, s[98:99]
	s_waitcnt lgkmcnt(3)
	v_mfma_f32_16x16x32_bf16 v[84:87], v[108:111], v[116:119], v[84:87]
	s_waitcnt lgkmcnt(1)
	v_mfma_f32_16x16x32_bf16 v[88:91], v[120:123], v[124:127], v[88:91]
	s_waitcnt lgkmcnt(0)
	v_mfma_f32_16x16x32_bf16 v[84:87], v[120:123], v[128:131], v[84:87]
	s_nop 7
	ds_write2_b32 v202, v88, v84 offset1:16
	ds_write2_b32 v202, v89, v85 offset0:68 offset1:84
	ds_write2_b32 v202, v90, v86 offset0:136 offset1:152
	s_add_u32 s98, s98, s100
	s_addc_u32 s99, s99, 0
	global_load_dword v249, v151, s[98:99]
	ds_write2_b32 v202, v91, v87 offset0:204 offset1:220
	ds_read2_b64 v[92:95], v224 offset1:4
	ds_read2_b64 v[100:103], v225 offset1:4
	ds_read2_b64 v[108:111], v226 offset1:4
	ds_read2_b64 v[116:119], v227 offset1:4
	ds_read2_b64 v[124:127], v224 offset0:8 offset1:12
	ds_read2_b64 v[128:131], v225 offset0:8 offset1:12
	ds_read2_b64 v[132:135], v226 offset0:8 offset1:12
	ds_read2_b64 v[136:139], v227 offset0:8 offset1:12
	v_cvt_pk_bf16_f32 v84, v4, v5
	s_add_u32 s98, s98, 0x2000
	s_addc_u32 s99, s99, 0
	global_load_dword v248, v151, s[98:99]
	v_cvt_pk_bf16_f32 v85, v6, v7
	v_cvt_pk_bf16_f32 v86, v12, v13
	v_cvt_pk_bf16_f32 v87, v14, v15
	v_cvt_pk_bf16_f32 v88, v8, v9
	v_cvt_pk_bf16_f32 v89, v10, v11
	v_cvt_pk_bf16_f32 v90, v16, v17
	v_cvt_pk_bf16_f32 v91, v18, v19
	ds_read2_b64 v[140:143], v224 offset0:16 offset1:20
	s_waitcnt lgkmcnt(8)
	v_mfma_f32_16x16x32_bf16 v[96:99], v[92:95], v[84:87], 0
	s_add_u32 s98, s98, 0x2000
	s_addc_u32 s99, s99, 0
	global_load_dword v247, v151, s[98:99]
	v_mfma_f32_16x16x32_bf16 v[92:95], v[92:95], v[88:91], 0
	ds_read2_b64 v[144:147], v225 offset0:16 offset1:20
	s_waitcnt lgkmcnt(8)
	v_mfma_f32_16x16x32_bf16 v[104:107], v[100:103], v[84:87], 0
	v_mfma_f32_16x16x32_bf16 v[100:103], v[100:103], v[88:91], 0
	s_waitcnt lgkmcnt(7)
	v_mfma_f32_16x16x32_bf16 v[112:115], v[108:111], v[84:87], 0
	v_mfma_f32_16x16x32_bf16 v[108:111], v[108:111], v[88:91], 0
	s_waitcnt lgkmcnt(6)
	v_mfma_f32_16x16x32_bf16 v[84:87], v[116:119], v[84:87], 0
	s_add_u32 s98, s98, 0x2000
	s_addc_u32 s99, s99, 0
	global_load_dword v246, v151, s[98:99]
	v_mfma_f32_16x16x32_bf16 v[88:91], v[116:119], v[88:91], 0
	v_cvt_pk_bf16_f32 v116, v20, v21
	v_cvt_pk_bf16_f32 v117, v22, v23
	v_cvt_pk_bf16_f32 v118, v28, v29
	v_cvt_pk_bf16_f32 v119, v30, v31
	v_cvt_pk_bf16_f32 v120, v24, v25
	v_cvt_pk_bf16_f32 v121, v26, v27
	v_cvt_pk_bf16_f32 v122, v32, v33
	v_cvt_pk_bf16_f32 v123, v34, v35
	s_waitcnt lgkmcnt(5)
	s_add_u32 s98, s98, 0x2000
	s_addc_u32 s99, s99, 0
	global_load_dword v245, v151, s[98:99]
	v_mfma_f32_16x16x32_bf16 v[96:99], v[124:127], v[116:119], v[96:99]
	v_mfma_f32_16x16x32_bf16 v[92:95], v[124:127], v[120:123], v[92:95]
	ds_read2_b64 v[124:127], v226 offset0:16 offset1:20
	s_waitcnt lgkmcnt(5)
	v_mfma_f32_16x16x32_bf16 v[104:107], v[128:131], v[116:119], v[104:107]
	v_mfma_f32_16x16x32_bf16 v[100:103], v[128:131], v[120:123], v[100:103]
	s_waitcnt lgkmcnt(4)
	v_mfma_f32_16x16x32_bf16 v[112:115], v[132:135], v[116:119], v[112:115]
	v_mfma_f32_16x16x32_bf16 v[108:111], v[132:135], v[120:123], v[108:111]
	s_waitcnt lgkmcnt(3)
	s_add_u32 s98, s98, 0x2000
	s_addc_u32 s99, s99, 0
	global_load_dword v244, v151, s[98:99]
	v_mfma_f32_16x16x32_bf16 v[84:87], v[136:139], v[116:119], v[84:87]
	v_cvt_pk_bf16_f32 v116, v36, v37
	v_cvt_pk_bf16_f32 v117, v38, v39
	v_cvt_pk_bf16_f32 v118, v44, v45
	v_mfma_f32_16x16x32_bf16 v[88:91], v[136:139], v[120:123], v[88:91]
	v_cvt_pk_bf16_f32 v119, v46, v47
	v_cvt_pk_bf16_f32 v120, v40, v41
	v_cvt_pk_bf16_f32 v121, v42, v43
	v_cvt_pk_bf16_f32 v122, v48, v49
	v_cvt_pk_bf16_f32 v123, v50, v51
	s_add_u32 s98, s98, 0x2000
	s_addc_u32 s99, s99, 0
	global_load_dword v243, v151, s[98:99]
	s_waitcnt lgkmcnt(2)
	v_mfma_f32_16x16x32_bf16 v[96:99], v[140:143], v[116:119], v[96:99]
	v_mfma_f32_16x16x32_bf16 v[92:95], v[140:143], v[120:123], v[92:95]
	s_waitcnt lgkmcnt(1)
	v_mfma_f32_16x16x32_bf16 v[104:107], v[144:147], v[116:119], v[104:107]
	v_mfma_f32_16x16x32_bf16 v[100:103], v[144:147], v[120:123], v[100:103]
	s_waitcnt lgkmcnt(0)
	v_mfma_f32_16x16x32_bf16 v[112:115], v[124:127], v[116:119], v[112:115]
	v_mfma_f32_16x16x32_bf16 v[108:111], v[124:127], v[120:123], v[108:111]
	ds_read2_b64 v[124:127], v227 offset0:16 offset1:20
	s_add_u32 s98, s98, 0x2000
	s_addc_u32 s99, s99, 0
	global_load_dword v242, v151, s[98:99]
	s_waitcnt lgkmcnt(0)
	v_mfma_f32_16x16x32_bf16 v[84:87], v[124:127], v[116:119], v[84:87]
	v_mfma_f32_16x16x32_bf16 v[116:119], v[124:127], v[120:123], v[88:91]
	ds_read2_b64 v[124:127], v224 offset0:24 offset1:28
	s_nop 1
	v_cvt_pk_bf16_f32 v88, v52, v53
	v_cvt_pk_bf16_f32 v89, v54, v55
	v_cvt_pk_bf16_f32 v90, v60, v61
	v_cvt_pk_bf16_f32 v91, v62, v63
	v_cvt_pk_bf16_f32 v120, v56, v57
	s_add_u32 s98, s98, 0x2000
	s_addc_u32 s99, s99, 0
	global_load_dword v241, v151, s[98:99]
	v_cvt_pk_bf16_f32 v121, v58, v59
	v_cvt_pk_bf16_f32 v122, v64, v65
	v_cvt_pk_bf16_f32 v123, v66, v67
	s_waitcnt lgkmcnt(0)
	v_mfma_f32_16x16x32_bf16 v[128:131], v[124:127], v[88:91], v[96:99]
	v_mfma_f32_16x16x32_bf16 v[124:127], v[124:127], v[120:123], v[92:95]
	s_nop 2
	ds_read2_b64 v[92:95], v225 offset0:24 offset1:28
	s_nop 2
	s_waitcnt lgkmcnt(0)
	s_add_u32 s98, s98, 0x2000
	s_addc_u32 s99, s99, 0
	global_load_dword v240, v151, s[98:99]
	v_mfma_f32_16x16x32_bf16 v[104:107], v[92:95], v[88:91], v[104:107]
	v_mfma_f32_16x16x32_bf16 v[132:135], v[92:95], v[120:123], v[100:103]
	ds_read2_b64 v[92:95], v226 offset0:24 offset1:28
	s_waitcnt lgkmcnt(0)
	v_mfma_f32_16x16x32_bf16 v[100:103], v[92:95], v[88:91], v[112:115]
	v_mfma_f32_16x16x32_bf16 v[96:99], v[92:95], v[120:123], v[108:111]
	ds_read2_b64 v[92:95], v227 offset0:24 offset1:28
	s_waitcnt lgkmcnt(0)
	v_mfma_f32_16x16x32_bf16 v[88:91], v[92:95], v[88:91], v[84:87]
	v_mfma_f32_16x16x32_bf16 v[92:95], v[92:95], v[120:123], v[116:119]
	s_add_u32 s98, s98, 0x2000
	s_addc_u32 s99, s99, 0
	global_load_dword v239, v151, s[98:99]
	v_add_u32_e32 v120, s33, v156
	s_nop 0
	ds_read_b128 v[84:87], v120
	ds_read_b128 v[136:139], v120 offset:64
	ds_read_b128 v[140:143], v120 offset:128
	s_nop 0
	s_waitcnt lgkmcnt(2)
	v_mul_f32_e32 v2, 0x3fb8aa3b, v84
	v_mul_f32_e32 v84, 0x3fb8aa3b, v86
	v_exp_f32_e32 v108, v84
	s_add_u32 s98, s98, 0x2000
	s_addc_u32 s99, s99, 0
	global_load_dword v238, v151, s[98:99]
	v_mul_f32_e32 v84, 0x3fb8aa3b, v87
	v_exp_f32_e32 v109, v84
	v_mul_f32_e32 v3, 0x3fb8aa3b, v85
	v_exp_f32_e32 v2, v2
	v_exp_f32_e32 v3, v3
	v_pk_mul_f32 v[86:87], v[130:131], v[108:109]
	v_pk_mul_f32 v[118:119], v[126:127], v[108:109]
	v_pk_mul_f32 v[84:85], v[128:129], v[2:3]
	v_pk_mul_f32 v[116:117], v[124:125], v[2:3]
	s_waitcnt lgkmcnt(1)
	s_add_u32 s98, s98, 0x2000
	s_addc_u32 s99, s99, 0
	global_load_dword v237, v151, s[98:99]
	v_mul_f32_e32 v2, 0x3fb8aa3b, v136
	v_mul_f32_e32 v108, 0x3fb8aa3b, v138
	v_mul_f32_e32 v3, 0x3fb8aa3b, v137
	v_exp_f32_e32 v112, v108
	v_mul_f32_e32 v108, 0x3fb8aa3b, v139
	v_exp_f32_e32 v2, v2
	v_exp_f32_e32 v3, v3
	v_exp_f32_e32 v113, v108
	v_pk_mul_f32 v[108:109], v[104:105], v[2:3]
	v_pk_mul_f32 v[110:111], v[106:107], v[112:113]
	s_add_u32 s98, s98, 0x2000
	s_addc_u32 s99, s99, 0
	global_load_dword v236, v151, s[98:99]
	v_pk_mul_f32 v[114:115], v[134:135], v[112:113]
	v_pk_mul_f32 v[112:113], v[132:133], v[2:3]
	s_waitcnt lgkmcnt(0)
	v_mul_f32_e32 v2, 0x3fb8aa3b, v140
	v_mul_f32_e32 v3, 0x3fb8aa3b, v141
	v_mul_f32_e32 v104, 0x3fb8aa3b, v142
	v_mul_f32_e32 v105, 0x3fb8aa3b, v143
	v_exp_f32_e32 v2, v2
	v_exp_f32_e32 v3, v3
	v_exp_f32_e32 v104, v104
	v_exp_f32_e32 v105, v105
	v_pk_mul_f32 v[100:101], v[100:101], v[2:3]
	v_pk_mul_f32 v[102:103], v[102:103], v[104:105]
	v_pk_mul_f32 v[106:107], v[98:99], v[104:105]
	v_pk_mul_f32 v[104:105], v[96:97], v[2:3]
	ds_read_b128 v[96:99], v120 offset:192
	s_waitcnt vmcnt(21)
	ds_write_b128 v230, v[76:79]
	s_waitcnt vmcnt(20)
	ds_write_b128 v230, v[80:83] offset:128
	s_waitcnt vmcnt(19)
	ds_write_b128 v230, v[72:75] offset:256
	s_waitcnt vmcnt(18)
	ds_write_b128 v230, v[68:71] offset:384
	s_waitcnt lgkmcnt(0)
	s_barrier
	v_mul_f32_e32 v2, 0x3fb8aa3b, v96
	v_mul_f32_e32 v3, 0x3fb8aa3b, v97
	v_mul_f32_e32 v96, 0x3fb8aa3b, v98
	v_mul_f32_e32 v97, 0x3fb8aa3b, v99
	v_exp_f32_e32 v2, v2
	v_exp_f32_e32 v3, v3
	v_exp_f32_e32 v96, v96
	v_exp_f32_e32 v97, v97
	v_pk_mul_f32 v[88:89], v[88:89], v[2:3]
	v_pk_mul_f32 v[90:91], v[90:91], v[96:97]
	v_pk_mul_f32 v[98:99], v[94:95], v[96:97]
	v_pk_mul_f32 v[96:97], v[92:93], v[2:3]
	v_mov_b32_e32 v2, s33
	ds_read_b32 v253, v2 offset:252
	ds_read_b128 v[148:151], v209
	ds_read_b128 v[140:143], v209 offset:16
	ds_read_b128 v[144:147], v201
	ds_read_b128 v[124:127], v201 offset:16
	ds_read_b128 v[120:123], v192 offset:53248
	s_waitcnt lgkmcnt(5)
	v_mul_f32_e32 v2, 0x3fb8aa3b, v253
	v_exp_f32_e32 v2, v2
	s_nop 0
	v_pk_mul_f32 v[6:7], v[6:7], v[2:3] op_sel_hi:[1,0]
	v_pk_mul_f32 v[4:5], v[4:5], v[2:3] op_sel_hi:[1,0]
	v_pk_mul_f32 v[74:75], v[10:11], v[2:3] op_sel_hi:[1,0]
	v_pk_mul_f32 v[72:73], v[8:9], v[2:3] op_sel_hi:[1,0]
	v_pk_mul_f32 v[10:11], v[14:15], v[2:3] op_sel_hi:[1,0]
	v_pk_mul_f32 v[8:9], v[12:13], v[2:3] op_sel_hi:[1,0]
	v_pk_mul_f32 v[18:19], v[18:19], v[2:3] op_sel_hi:[1,0]
	v_pk_mul_f32 v[16:17], v[16:17], v[2:3] op_sel_hi:[1,0]
	v_pk_mul_f32 v[14:15], v[22:23], v[2:3] op_sel_hi:[1,0]
	v_pk_mul_f32 v[12:13], v[20:21], v[2:3] op_sel_hi:[1,0]
	v_pk_mul_f32 v[26:27], v[26:27], v[2:3] op_sel_hi:[1,0]
	v_pk_mul_f32 v[24:25], v[24:25], v[2:3] op_sel_hi:[1,0]
	v_pk_mul_f32 v[22:23], v[30:31], v[2:3] op_sel_hi:[1,0]
	v_pk_mul_f32 v[20:21], v[28:29], v[2:3] op_sel_hi:[1,0]
	v_pk_mul_f32 v[34:35], v[34:35], v[2:3] op_sel_hi:[1,0]
	v_pk_mul_f32 v[32:33], v[32:33], v[2:3] op_sel_hi:[1,0]
	v_pk_mul_f32 v[30:31], v[38:39], v[2:3] op_sel_hi:[1,0]
	v_pk_mul_f32 v[28:29], v[36:37], v[2:3] op_sel_hi:[1,0]
	v_pk_mul_f32 v[42:43], v[42:43], v[2:3] op_sel_hi:[1,0]
	v_pk_mul_f32 v[40:41], v[40:41], v[2:3] op_sel_hi:[1,0]
	v_pk_mul_f32 v[38:39], v[46:47], v[2:3] op_sel_hi:[1,0]
	v_pk_mul_f32 v[36:37], v[44:45], v[2:3] op_sel_hi:[1,0]
	v_pk_mul_f32 v[50:51], v[50:51], v[2:3] op_sel_hi:[1,0]
	v_pk_mul_f32 v[48:49], v[48:49], v[2:3] op_sel_hi:[1,0]
	v_pk_mul_f32 v[46:47], v[54:55], v[2:3] op_sel_hi:[1,0]
	v_pk_mul_f32 v[44:45], v[52:53], v[2:3] op_sel_hi:[1,0]
	v_pk_mul_f32 v[58:59], v[58:59], v[2:3] op_sel_hi:[1,0]
	v_pk_mul_f32 v[56:57], v[56:57], v[2:3] op_sel_hi:[1,0]
	v_pk_mul_f32 v[54:55], v[62:63], v[2:3] op_sel_hi:[1,0]
	v_pk_mul_f32 v[52:53], v[60:61], v[2:3] op_sel_hi:[1,0]
	v_pk_mul_f32 v[62:63], v[66:67], v[2:3] op_sel_hi:[1,0]
	v_pk_mul_f32 v[60:61], v[64:65], v[2:3] op_sel_hi:[1,0]
	ds_read_b128 v[64:67], v192 offset:55552
	ds_read_b32 v2, v229
	ds_read_b128 v[68:71], v232
	ds_read_b128 v[76:79], v232 offset:16
	s_waitcnt lgkmcnt(2)
	v_sub_f32_e32 v3, v2, v148
	v_mul_f32_e32 v3, 0x3fb8aa3b, v3
	v_exp_f32_e32 v3, v3
	s_waitcnt lgkmcnt(1)
	v_mul_f32_e32 v3, v68, v3
	v_sub_f32_e32 v68, v2, v149
	v_mul_f32_e32 v68, 0x3fb8aa3b, v68
	v_exp_f32_e32 v68, v68
	v_mul_f32_e32 v3, v144, v3
	v_cndmask_b32_e64 v3, v3, 0, s[24:25]
	v_mul_f32_e32 v68, v69, v68
	v_sub_f32_e32 v69, v2, v150
	v_mul_f32_e32 v69, 0x3fb8aa3b, v69
	v_exp_f32_e32 v69, v69
	v_mul_f32_e32 v68, v145, v68
	v_cndmask_b32_e64 v68, 0, v68, s[26:27]
	ds_read_b32 v80, v229 offset:64
	ds_read_b128 v[128:131], v232 offset:4352
	ds_read_b128 v[132:135], v232 offset:4368
	v_cvt_pk_bf16_f32 v68, v3, v68
	v_mul_f32_e32 v69, v70, v69
	v_sub_f32_e32 v70, v2, v151
	v_mul_f32_e32 v70, 0x3fb8aa3b, v70
	v_exp_f32_e32 v70, v70
	v_mul_f32_e32 v69, v146, v69
	v_cndmask_b32_e64 v69, v69, 0, s[28:29]
	v_mul_f32_e32 v70, v71, v70
	v_sub_f32_e32 v71, v2, v140
	v_mul_f32_e32 v71, 0x3fb8aa3b, v71
	v_exp_f32_e32 v71, v71
	v_mul_f32_e32 v70, v147, v70
	v_cndmask_b32_e64 v70, v70, 0, s[30:31]
	v_cvt_pk_bf16_f32 v69, v69, v70
	s_waitcnt lgkmcnt(3)
	v_mul_f32_e32 v71, v76, v71
	v_sub_f32_e32 v76, v2, v141
	v_mul_f32_e32 v76, 0x3fb8aa3b, v76
	v_exp_f32_e32 v76, v76
	v_mul_f32_e32 v71, v124, v71
	v_cndmask_b32_e64 v71, v71, 0, s[34:35]
	v_mul_f32_e32 v76, v77, v76
	v_sub_f32_e32 v77, v2, v142
	v_sub_f32_e32 v2, v2, v143
	v_mul_f32_e32 v77, 0x3fb8aa3b, v77
	v_mul_f32_e32 v2, 0x3fb8aa3b, v2
	v_exp_f32_e32 v77, v77
	v_exp_f32_e32 v2, v2
	v_mul_f32_e32 v76, v125, v76
	v_cndmask_b32_e64 v76, v76, 0, s[36:37]
	v_mul_f32_e32 v77, v78, v77
	v_mul_f32_e32 v2, v79, v2
	v_mul_f32_e32 v77, v126, v77
	v_mul_f32_e32 v2, v127, v2
	v_cndmask_b32_e64 v77, v77, 0, s[38:39]
	v_cndmask_b32_e64 v2, v2, 0, s[40:41]
	v_cvt_pk_bf16_f32 v70, v71, v76
	v_cvt_pk_bf16_f32 v71, v77, v2
	s_nop 0
	s_nop 0
	v_mfma_f32_16x16x32_bf16 v[92:95], v[68:71], v[120:123], v[84:87]
	v_mfma_f32_16x16x32_bf16 v[84:87], v[68:71], v[64:67], v[116:119]
	s_waitcnt lgkmcnt(2)
	v_sub_f32_e32 v3, v80, v148
	v_mul_f32_e32 v3, 0x3fb8aa3b, v3
	v_exp_f32_e32 v3, v3
	s_waitcnt lgkmcnt(1)
	v_mul_f32_e32 v3, v128, v3
	v_sub_f32_e32 v68, v80, v149
	v_mul_f32_e32 v68, 0x3fb8aa3b, v68
	v_exp_f32_e32 v68, v68
	v_mul_f32_e32 v3, v144, v3
	v_cndmask_b32_e64 v3, v3, 0, s[42:43]
	v_mul_f32_e32 v68, v129, v68
	v_sub_f32_e32 v69, v80, v150
	v_mul_f32_e32 v69, 0x3fb8aa3b, v69
	v_exp_f32_e32 v69, v69
	v_mul_f32_e32 v68, v145, v68
	ds_read_b32 v116, v229 offset:128
	ds_read_b128 v[136:139], v232 offset:8704
	v_cndmask_b32_e64 v68, 0, v68, s[44:45]
	v_cvt_pk_bf16_f32 v68, v3, v68
	v_mul_f32_e32 v69, v130, v69
	v_sub_f32_e32 v70, v80, v151
	v_mul_f32_e32 v70, 0x3fb8aa3b, v70
	v_exp_f32_e32 v70, v70
	v_mul_f32_e32 v69, v146, v69
	v_cndmask_b32_e64 v69, v69, 0, s[46:47]
	v_mul_f32_e32 v70, v131, v70
	v_sub_f32_e32 v71, v80, v140
	v_mul_f32_e32 v71, 0x3fb8aa3b, v71
	v_exp_f32_e32 v71, v71
	v_mul_f32_e32 v70, v147, v70
	v_cndmask_b32_e64 v70, v70, 0, s[48:49]
	v_cvt_pk_bf16_f32 v69, v69, v70
	s_waitcnt lgkmcnt(2)
	v_mul_f32_e32 v71, v132, v71
	v_sub_f32_e32 v76, v80, v141
	v_mul_f32_e32 v76, 0x3fb8aa3b, v76
	v_exp_f32_e32 v76, v76
	v_mul_f32_e32 v71, v124, v71
	v_cndmask_b32_e64 v71, v71, 0, s[50:51]
	v_mul_f32_e32 v76, v133, v76
	v_sub_f32_e32 v77, v80, v142
	v_sub_f32_e32 v2, v80, v143
	v_mul_f32_e32 v77, 0x3fb8aa3b, v77
	v_mul_f32_e32 v2, 0x3fb8aa3b, v2
	v_exp_f32_e32 v77, v77
	v_exp_f32_e32 v2, v2
	v_mul_f32_e32 v76, v125, v76
	v_cndmask_b32_e64 v76, v76, 0, s[52:53]
	v_mul_f32_e32 v77, v134, v77
	v_mul_f32_e32 v2, v135, v2
	v_mul_f32_e32 v77, v126, v77
	v_mul_f32_e32 v2, v127, v2
	v_cndmask_b32_e64 v77, v77, 0, s[54:55]
	v_cndmask_b32_e64 v2, v2, 0, s[56:57]
	v_cvt_pk_bf16_f32 v70, v71, v76
	v_cvt_pk_bf16_f32 v71, v77, v2
	s_nop 0
	s_nop 0
	v_mfma_f32_16x16x32_bf16 v[76:79], v[68:71], v[120:123], v[108:111]
	s_nop 2
	ds_read_b128 v[108:111], v232 offset:8720
	s_nop 0
	s_waitcnt lgkmcnt(2)
	v_sub_f32_e32 v3, v116, v148
	v_mul_f32_e32 v3, 0x3fb8aa3b, v3
	v_exp_f32_e32 v3, v3
	v_mfma_f32_16x16x32_bf16 v[68:71], v[68:71], v[64:67], v[112:115]
	s_waitcnt lgkmcnt(1)
	v_mul_f32_e32 v3, v136, v3
	v_sub_f32_e32 v80, v116, v149
	v_mul_f32_e32 v80, 0x3fb8aa3b, v80
	v_exp_f32_e32 v80, v80
	ds_read_b32 v112, v229 offset:192
	ds_read_b128 v[128:131], v232 offset:13056
	v_mul_f32_e32 v3, v144, v3
	v_mul_f32_e32 v80, v137, v80
	v_sub_f32_e32 v81, v116, v150
	v_mul_f32_e32 v81, 0x3fb8aa3b, v81
	v_exp_f32_e32 v81, v81
	v_mul_f32_e32 v80, v145, v80
	v_cvt_pk_bf16_f32 v80, v3, v80
	v_mul_f32_e32 v81, v138, v81
	v_sub_f32_e32 v82, v116, v151
	v_mul_f32_e32 v82, 0x3fb8aa3b, v82
	v_exp_f32_e32 v82, v82
	v_mul_f32_e32 v81, v146, v81
	v_mul_f32_e32 v82, v139, v82
	v_sub_f32_e32 v83, v116, v140
	v_mul_f32_e32 v83, 0x3fb8aa3b, v83
	v_exp_f32_e32 v83, v83
	v_mul_f32_e32 v82, v147, v82
	v_cvt_pk_bf16_f32 v81, v81, v82
	s_waitcnt lgkmcnt(2)
	v_mul_f32_e32 v83, v108, v83
	v_sub_f32_e32 v108, v116, v141
	v_mul_f32_e32 v108, 0x3fb8aa3b, v108
	v_exp_f32_e32 v108, v108
	v_mul_f32_e32 v83, v124, v83
	v_mul_f32_e32 v108, v109, v108
	v_sub_f32_e32 v109, v116, v142
	v_sub_f32_e32 v2, v116, v143
	v_mul_f32_e32 v109, 0x3fb8aa3b, v109
	v_mul_f32_e32 v2, 0x3fb8aa3b, v2
	v_exp_f32_e32 v109, v109
	v_exp_f32_e32 v2, v2
	v_mul_f32_e32 v108, v125, v108
	v_cvt_pk_bf16_f32 v82, v83, v108
	v_mul_f32_e32 v109, v110, v109
	v_mul_f32_e32 v2, v111, v2
	v_mul_f32_e32 v109, v126, v109
	v_mul_f32_e32 v2, v127, v2
	v_cvt_pk_bf16_f32 v83, v109, v2
	s_nop 0
	s_nop 0
	v_mfma_f32_16x16x32_bf16 v[132:135], v[80:83], v[120:123], v[100:103]
	s_nop 2
	ds_read_b128 v[100:103], v232 offset:13072
	v_mfma_f32_16x16x32_bf16 v[136:139], v[80:83], v[64:67], v[104:107]
	s_waitcnt lgkmcnt(2)
	v_sub_f32_e32 v3, v112, v148
	v_mul_f32_e32 v3, 0x3fb8aa3b, v3
	v_exp_f32_e32 v3, v3
	s_waitcnt lgkmcnt(1)
	v_mul_f32_e32 v3, v128, v3
	v_sub_f32_e32 v80, v112, v149
	v_mul_f32_e32 v80, 0x3fb8aa3b, v80
	v_exp_f32_e32 v80, v80
	v_mul_f32_e32 v3, v144, v3
	v_mul_f32_e32 v80, v129, v80
	v_sub_f32_e32 v81, v112, v150
	v_mul_f32_e32 v81, 0x3fb8aa3b, v81
	v_exp_f32_e32 v81, v81
	v_mul_f32_e32 v80, v145, v80
	v_mul_f32_e32 v81, v130, v81
	v_sub_f32_e32 v82, v112, v151
	v_mul_f32_e32 v82, 0x3fb8aa3b, v82
	v_exp_f32_e32 v82, v82
	v_mul_f32_e32 v81, v146, v81
	v_mul_f32_e32 v82, v131, v82
	v_sub_f32_e32 v83, v112, v140
	v_mul_f32_e32 v83, 0x3fb8aa3b, v83
	v_exp_f32_e32 v83, v83
	v_mul_f32_e32 v82, v147, v82
	s_waitcnt lgkmcnt(0)
	v_mul_f32_e32 v83, v100, v83
	v_sub_f32_e32 v100, v112, v141
	v_mul_f32_e32 v100, 0x3fb8aa3b, v100
	v_exp_f32_e32 v100, v100
	v_mul_f32_e32 v83, v124, v83
	v_mul_f32_e32 v100, v101, v100
	v_mul_f32_e32 v104, v125, v100
	v_sub_f32_e32 v100, v112, v142
	v_sub_f32_e32 v2, v112, v143
	v_mul_f32_e32 v100, 0x3fb8aa3b, v100
	v_mul_f32_e32 v2, 0x3fb8aa3b, v2
	v_exp_f32_e32 v100, v100
	v_exp_f32_e32 v2, v2
	v_mul_f32_e32 v100, v102, v100
	v_mul_f32_e32 v2, v103, v2
	v_mul_f32_e32 v105, v126, v100
	v_mul_f32_e32 v2, v127, v2
	v_cvt_pk_bf16_f32 v100, v3, v80
	v_cvt_pk_bf16_f32 v101, v81, v82
	v_cvt_pk_bf16_f32 v102, v83, v104
	v_cvt_pk_bf16_f32 v103, v105, v2
	v_sub_f32_e32 v2, v253, v148
	s_nop 0
	v_mfma_f32_16x16x32_bf16 v[80:83], v[100:103], v[120:123], v[88:91]
	v_sub_f32_e32 v3, v253, v149
	v_mul_f32_e32 v2, 0x3fb8aa3b, v2
	v_mul_f32_e32 v3, 0x3fb8aa3b, v3
	v_sub_f32_e32 v88, v253, v150
	v_mul_f32_e32 v88, 0x3fb8aa3b, v88
	v_exp_f32_e32 v88, v88
	v_mfma_f32_16x16x32_bf16 v[128:131], v[100:103], v[64:67], v[96:99]
	v_exp_f32_e32 v2, v2
	v_exp_f32_e32 v3, v3
	v_and_b32_e32 v89, 0xffff0000, v120
	v_mul_f32_e32 v96, v146, v88
	v_sub_f32_e32 v88, v253, v151
	v_mul_f32_e32 v88, 0x3fb8aa3b, v88
	v_exp_f32_e32 v88, v88
	v_mul_f32_e32 v2, v144, v2
	v_mul_f32_e32 v3, v145, v3
	v_lshlrev_b32_e32 v90, 16, v121
	v_mul_f32_e32 v97, v147, v88
	v_sub_f32_e32 v88, v253, v140
	v_mul_f32_e32 v88, 0x3fb8aa3b, v88
	v_exp_f32_e32 v88, v88
	v_lshlrev_b32_e32 v102, 16, v122
	v_mul_f32_e32 v89, v3, v89
	v_mul_f32_e32 v90, v96, v90
	v_mul_f32_e32 v98, v124, v88
	v_sub_f32_e32 v88, v253, v141
	v_mul_f32_e32 v88, 0x3fb8aa3b, v88
	v_exp_f32_e32 v88, v88
	v_and_b32_e32 v91, 0xffff0000, v121
	v_mul_f32_e32 v102, v98, v102
	v_and_b32_e32 v103, 0xffff0000, v122
	v_mul_f32_e32 v99, v125, v88
	ds_read_b128 v[106:109], v233 offset:34816
	v_sub_f32_e32 v88, v253, v142
	v_mul_f32_e32 v88, 0x3fb8aa3b, v88
	ds_read_b128 v[110:113], v233 offset:37120
	v_exp_f32_e32 v88, v88
	v_mul_f32_e32 v91, v97, v91
	ds_read_b128 v[114:117], v233 offset:39424
	v_mul_f32_e32 v103, v99, v103
	v_lshlrev_b32_e32 v104, 16, v123
	ds_read_b128 v[144:147], v233 offset:41728
	v_mul_f32_e32 v100, v126, v88
	v_sub_f32_e32 v88, v253, v143
	ds_read_b128 v[148:151], v233 offset:44032
	v_mul_f32_e32 v88, 0x3fb8aa3b, v88
	v_exp_f32_e32 v88, v88
	v_and_b32_e32 v105, 0xffff0000, v123
	v_mul_f32_e32 v104, v100, v104
	v_mul_f32_e32 v101, v127, v88
	v_lshlrev_b32_e32 v88, 16, v120
	v_mul_f32_e32 v88, v2, v88
	v_cvt_pk_bf16_f32 v88, v88, v89
	v_cvt_pk_bf16_f32 v89, v90, v91
	v_cvt_pk_bf16_f32 v90, v102, v103
	v_lshlrev_b32_e32 v102, 16, v64
	v_and_b32_e32 v64, 0xffff0000, v64
	v_mul_f32_e32 v3, v3, v64
	v_lshlrev_b32_e32 v64, 16, v65
	v_mul_f32_e32 v64, v96, v64
	v_lshlrev_b32_e32 v96, 16, v66
	v_and_b32_e32 v65, 0xffff0000, v65
	v_mul_f32_e32 v98, v98, v96
	v_and_b32_e32 v66, 0xffff0000, v66
	v_lshlrev_b32_e32 v96, 16, v67
	v_and_b32_e32 v67, 0xffff0000, v67
	v_mul_f32_e32 v65, v97, v65
	v_mul_f32_e32 v66, v99, v66
	v_mul_f32_e32 v99, v100, v96
	v_mul_f32_e32 v67, v101, v67
	v_mul_f32_e32 v105, v101, v105
	v_cvt_pk_bf16_f32 v91, v104, v105
	v_mul_f32_e32 v2, v2, v102
	v_cvt_pk_bf16_f32 v96, v2, v3
	v_cvt_pk_bf16_f32 v97, v64, v65
	v_cvt_pk_bf16_f32 v98, v98, v66
	v_cvt_pk_bf16_f32 v99, v99, v67
	s_waitcnt lgkmcnt(4)
	v_mfma_f32_16x16x32_bf16 v[2:5], v[106:109], v[88:91], v[4:7]
	v_mfma_f32_16x16x32_bf16 v[140:143], v[106:109], v[96:99], v[72:75]
	s_waitcnt lgkmcnt(3)
	v_mfma_f32_16x16x32_bf16 v[120:123], v[110:113], v[88:91], v[8:11]
	s_nop 2
	ds_read_b128 v[6:9], v233 offset:46336
	s_nop 2
	s_waitcnt lgkmcnt(3)
	v_mfma_f32_16x16x32_bf16 v[124:127], v[114:117], v[88:91], v[12:15]
	v_mfma_f32_16x16x32_bf16 v[24:27], v[114:117], v[96:99], v[24:27]
	s_waitcnt lgkmcnt(2)
	v_mfma_f32_16x16x32_bf16 v[116:119], v[144:147], v[88:91], v[20:23]
	v_mfma_f32_16x16x32_bf16 v[32:35], v[144:147], v[96:99], v[32:35]
	v_mfma_f32_16x16x32_bf16 v[16:19], v[110:113], v[96:99], v[16:19]
	s_waitcnt lgkmcnt(1)
	v_mfma_f32_16x16x32_bf16 v[64:67], v[148:151], v[88:91], v[28:31]
	v_mfma_f32_16x16x32_bf16 v[40:43], v[148:151], v[96:99], v[40:43]
	s_waitcnt lgkmcnt(0)
	v_mfma_f32_16x16x32_bf16 v[100:103], v[6:9], v[88:91], v[36:39]
	v_mfma_f32_16x16x32_bf16 v[48:51], v[6:9], v[96:99], v[48:51]
	ds_read_b128 v[6:9], v233 offset:48640
	s_waitcnt lgkmcnt(0)
	v_mfma_f32_16x16x32_bf16 v[104:107], v[6:9], v[88:91], v[44:47]
	v_mfma_f32_16x16x32_bf16 v[56:59], v[6:9], v[96:99], v[56:59]
	ds_read_b128 v[6:9], v233 offset:50944
	s_nop 0
	ds_read_b128 v[44:47], v209 offset:128
	ds_read_b128 v[28:31], v209 offset:144
	ds_read_b128 v[36:39], v201 offset:128
	ds_read_b128 v[20:23], v201 offset:144
	ds_read_b128 v[10:13], v192 offset:53312
	s_waitcnt lgkmcnt(5)
	v_mfma_f32_16x16x32_bf16 v[108:111], v[6:9], v[88:91], v[52:55]
	v_mfma_f32_16x16x32_bf16 v[112:115], v[6:9], v[96:99], v[60:63]
	ds_read_b128 v[6:9], v192 offset:55616
	ds_read_b32 v14, v229 offset:128
	ds_read_b128 v[52:55], v232 offset:8832
	ds_read_b128 v[60:63], v232 offset:8848
	s_waitcnt lgkmcnt(2)
	v_sub_f32_e32 v15, v14, v44
	v_mul_f32_e32 v15, 0x3fb8aa3b, v15
	v_exp_f32_e32 v15, v15
	s_waitcnt lgkmcnt(1)
	v_mul_f32_e32 v15, v52, v15
	v_sub_f32_e32 v52, v14, v45
	v_mul_f32_e32 v52, 0x3fb8aa3b, v52
	v_exp_f32_e32 v52, v52
	v_mul_f32_e32 v15, v36, v15
	v_cndmask_b32_e64 v15, v15, 0, s[24:25]
	v_mul_f32_e32 v52, v53, v52
	v_sub_f32_e32 v53, v14, v46
	v_mul_f32_e32 v53, 0x3fb8aa3b, v53
	v_exp_f32_e32 v53, v53
	v_mul_f32_e32 v52, v37, v52
	v_cndmask_b32_e64 v52, v52, 0, s[58:59]
	ds_read_b32 v72, v229 offset:192
	ds_read_b128 v[144:147], v232 offset:13184
	ds_read_b128 v[148:151], v232 offset:13200
	v_cvt_pk_bf16_f32 v52, v15, v52
	v_mul_f32_e32 v53, v54, v53
	v_sub_f32_e32 v54, v14, v47
	v_mul_f32_e32 v54, 0x3fb8aa3b, v54
	v_exp_f32_e32 v54, v54
	v_mul_f32_e32 v53, v38, v53
	v_cndmask_b32_e64 v53, v53, 0, s[60:61]
	v_mul_f32_e32 v54, v55, v54
	v_sub_f32_e32 v55, v14, v28
	v_mul_f32_e32 v55, 0x3fb8aa3b, v55
	v_exp_f32_e32 v55, v55
	v_mul_f32_e32 v54, v39, v54
	v_cndmask_b32_e64 v54, v54, 0, s[62:63]
	v_cvt_pk_bf16_f32 v53, v53, v54
	s_waitcnt lgkmcnt(3)
	v_mul_f32_e32 v55, v60, v55
	v_sub_f32_e32 v60, v14, v29
	v_mul_f32_e32 v60, 0x3fb8aa3b, v60
	v_exp_f32_e32 v60, v60
	v_mul_f32_e32 v55, v20, v55
	v_cndmask_b32_e64 v55, v55, 0, s[64:65]
	v_mul_f32_e32 v60, v61, v60
	v_sub_f32_e32 v61, v14, v30
	v_sub_f32_e32 v14, v14, v31
	v_mul_f32_e32 v61, 0x3fb8aa3b, v61
	v_mul_f32_e32 v14, 0x3fb8aa3b, v14
	v_exp_f32_e32 v61, v61
	v_exp_f32_e32 v14, v14
	v_mul_f32_e32 v60, v21, v60
	v_cndmask_b32_e64 v60, v60, 0, s[66:67]
	v_mul_f32_e32 v61, v62, v61
	v_mul_f32_e32 v14, v63, v14
	v_mul_f32_e32 v61, v22, v61
	v_mul_f32_e32 v14, v23, v14
	v_cndmask_b32_e64 v61, v61, 0, s[68:69]
	v_cndmask_b32_e64 v14, v14, 0, s[70:71]
	v_cvt_pk_bf16_f32 v54, v55, v60
	v_cvt_pk_bf16_f32 v55, v61, v14
	s_nop 0
	s_nop 0
	v_mfma_f32_16x16x32_bf16 v[96:99], v[52:55], v[10:13], v[132:135]
	v_mfma_f32_16x16x32_bf16 v[88:91], v[52:55], v[6:9], v[136:139]
	s_waitcnt lgkmcnt(2)
	v_sub_f32_e32 v15, v72, v44
	v_mul_f32_e32 v15, 0x3fb8aa3b, v15
	v_exp_f32_e32 v15, v15
	s_waitcnt lgkmcnt(1)
	v_mul_f32_e32 v15, v144, v15
	v_sub_f32_e32 v52, v72, v45
	v_mul_f32_e32 v52, 0x3fb8aa3b, v52
	v_exp_f32_e32 v52, v52
	v_mul_f32_e32 v15, v36, v15
	v_cndmask_b32_e64 v15, v15, 0, s[72:73]
	v_mul_f32_e32 v52, v145, v52
	v_sub_f32_e32 v53, v72, v46
	v_mul_f32_e32 v53, 0x3fb8aa3b, v53
	v_exp_f32_e32 v53, v53
	v_mul_f32_e32 v52, v37, v52
	v_cndmask_b32_e64 v52, v52, 0, s[74:75]
	v_cvt_pk_bf16_f32 v52, v15, v52
	v_mul_f32_e32 v53, v146, v53
	v_sub_f32_e32 v54, v72, v47
	v_mul_f32_e32 v54, 0x3fb8aa3b, v54
	v_exp_f32_e32 v54, v54
	v_mul_f32_e32 v53, v38, v53
	v_cndmask_b32_e64 v53, v53, 0, s[76:77]
	v_sub_f32_e32 v15, v253, v45
	v_mul_f32_e32 v54, v147, v54
	v_sub_f32_e32 v55, v72, v28
	v_mul_f32_e32 v55, 0x3fb8aa3b, v55
	v_exp_f32_e32 v55, v55
	v_sub_f32_e32 v28, v253, v28
	v_mul_f32_e32 v28, 0x3fb8aa3b, v28
	v_exp_f32_e32 v28, v28
	s_waitcnt lgkmcnt(0)
	v_mul_f32_e32 v55, v148, v55
	v_sub_f32_e32 v60, v72, v29
	v_mul_f32_e32 v60, 0x3fb8aa3b, v60
	v_exp_f32_e32 v60, v60
	v_mul_f32_e32 v55, v20, v55
	v_mul_f32_e32 v20, v20, v28
	v_sub_f32_e32 v28, v253, v29
	v_mul_f32_e32 v60, v149, v60
	v_sub_f32_e32 v61, v72, v30
	v_sub_f32_e32 v14, v72, v31
	v_mul_f32_e32 v14, 0x3fb8aa3b, v14
	v_mul_f32_e32 v61, 0x3fb8aa3b, v61
	v_exp_f32_e32 v14, v14
	v_exp_f32_e32 v61, v61
	v_mul_f32_e32 v28, 0x3fb8aa3b, v28
	v_exp_f32_e32 v28, v28
	v_mul_f32_e32 v14, v151, v14
	v_mul_f32_e32 v54, v39, v54
	v_mul_f32_e32 v61, v150, v61
	v_mul_f32_e32 v14, v23, v14
	v_cndmask_b32_e64 v54, v54, 0, s[78:79]
	v_cndmask_b32_e64 v55, v55, 0, s[80:81]
	v_mul_f32_e32 v60, v21, v60
	v_mul_f32_e32 v61, v22, v61
	v_cndmask_b32_e64 v14, v14, 0, s[86:87]
	v_mul_f32_e32 v21, v21, v28
	v_sub_f32_e32 v28, v253, v30
	v_cndmask_b32_e64 v60, v60, 0, s[82:83]
	v_cndmask_b32_e64 v61, v61, 0, s[84:85]
	v_cvt_pk_bf16_f32 v53, v53, v54
	v_cvt_pk_bf16_f32 v54, v55, v60
	v_cvt_pk_bf16_f32 v55, v61, v14
	v_sub_f32_e32 v14, v253, v44
	v_mul_f32_e32 v15, 0x3fb8aa3b, v15
	v_mul_f32_e32 v28, 0x3fb8aa3b, v28
	v_mul_f32_e32 v14, 0x3fb8aa3b, v14
	v_exp_f32_e32 v15, v15
	v_exp_f32_e32 v28, v28
	v_exp_f32_e32 v14, v14
	v_mfma_f32_16x16x32_bf16 v[80:83], v[52:55], v[10:13], v[80:83]
	v_mul_f32_e32 v15, v37, v15
	v_sub_f32_e32 v37, v253, v47
	v_mul_f32_e32 v22, v22, v28
	v_sub_f32_e32 v28, v253, v31
	v_mul_f32_e32 v14, v36, v14
	v_sub_f32_e32 v36, v253, v46
	v_mul_f32_e32 v37, 0x3fb8aa3b, v37
	v_mul_f32_e32 v28, 0x3fb8aa3b, v28
	v_mul_f32_e32 v36, 0x3fb8aa3b, v36
	v_exp_f32_e32 v37, v37
	v_exp_f32_e32 v28, v28
	v_exp_f32_e32 v36, v36
	v_lshlrev_b32_e32 v29, 16, v11
	v_mul_f32_e32 v37, v39, v37
	v_mul_f32_e32 v23, v23, v28
	v_lshlrev_b32_e32 v28, 16, v10
	ds_read_b128 v[132:135], v233 offset:34880
	ds_read_b128 v[136:139], v233 offset:37184
	ds_read_b128 v[144:147], v233 offset:39488
	ds_read_b128 v[148:151], v233 offset:41792
	ds_read_b128 v[44:47], v233 offset:44096
	v_and_b32_e32 v10, 0xffff0000, v10
	v_and_b32_e32 v11, 0xffff0000, v11
	v_lshlrev_b32_e32 v30, 16, v12
	v_and_b32_e32 v12, 0xffff0000, v12
	v_lshlrev_b32_e32 v31, 16, v13
	v_and_b32_e32 v13, 0xffff0000, v13
	v_mul_f32_e32 v36, v38, v36
	v_mul_f32_e32 v10, v15, v10
	v_mul_f32_e32 v11, v37, v11
	v_mul_f32_e32 v12, v21, v12
	v_mul_f32_e32 v13, v23, v13
	v_mfma_f32_16x16x32_bf16 v[72:75], v[52:55], v[6:9], v[128:131]
	ds_read_b128 v[52:55], v233 offset:46400
	v_mul_f32_e32 v28, v14, v28
	v_mul_f32_e32 v29, v36, v29
	v_mul_f32_e32 v30, v20, v30
	v_mul_f32_e32 v31, v22, v31
	v_cvt_pk_bf16_f32 v60, v28, v10
	v_cvt_pk_bf16_f32 v61, v29, v11
	v_cvt_pk_bf16_f32 v62, v30, v12
	v_cvt_pk_bf16_f32 v63, v31, v13
	v_lshlrev_b32_e32 v10, 16, v6
	v_lshlrev_b32_e32 v11, 16, v7
	v_lshlrev_b32_e32 v12, 16, v8
	v_and_b32_e32 v8, 0xffff0000, v8
	v_lshlrev_b32_e32 v13, 16, v9
	v_and_b32_e32 v9, 0xffff0000, v9
	v_mul_f32_e32 v10, v14, v10
	v_and_b32_e32 v6, 0xffff0000, v6
	v_mul_f32_e32 v11, v36, v11
	v_and_b32_e32 v7, 0xffff0000, v7
	v_mul_f32_e32 v8, v21, v8
	v_mul_f32_e32 v9, v23, v9
	v_mul_f32_e32 v6, v15, v6
	v_mul_f32_e32 v7, v37, v7
	v_mul_f32_e32 v12, v20, v12
	v_mul_f32_e32 v13, v22, v13
	v_cvt_pk_bf16_f32 v128, v10, v6
	v_cvt_pk_bf16_f32 v129, v11, v7
	v_cvt_pk_bf16_f32 v130, v12, v8
	v_cvt_pk_bf16_f32 v131, v13, v9
	s_waitcnt lgkmcnt(4)
	v_mfma_f32_16x16x32_bf16 v[12:15], v[136:139], v[60:63], v[120:123]
	v_mfma_f32_16x16x32_bf16 v[16:19], v[136:139], v[128:131], v[16:19]
	s_waitcnt lgkmcnt(3)
	v_mfma_f32_16x16x32_bf16 v[20:23], v[144:147], v[60:63], v[124:127]
	v_mfma_f32_16x16x32_bf16 v[24:27], v[144:147], v[128:131], v[24:27]
	s_waitcnt lgkmcnt(2)
	v_mfma_f32_16x16x32_bf16 v[28:31], v[148:151], v[60:63], v[116:119]
	v_mfma_f32_16x16x32_bf16 v[32:35], v[148:151], v[128:131], v[32:35]
	s_waitcnt lgkmcnt(1)
	v_mfma_f32_16x16x32_bf16 v[36:39], v[44:47], v[60:63], v[64:67]
	s_nop 2
	ds_read_b128 v[64:67], v233 offset:48704
	s_nop 2
	v_mfma_f32_16x16x32_bf16 v[4:7], v[132:135], v[60:63], v[2:5]
	s_nop 2
	ds_read_b64 v[2:3], v234 offset:53248
	ds_read_u16 v192, v235
	v_mfma_f32_16x16x32_bf16 v[40:43], v[44:47], v[128:131], v[40:43]
	s_nop 1
	s_waitcnt lgkmcnt(3)
	v_mfma_f32_16x16x32_bf16 v[44:47], v[52:55], v[60:63], v[100:103]
	s_nop 2
	ds_read_u16 v103, v235 offset:528
	v_mfma_f32_16x16x32_bf16 v[48:51], v[52:55], v[128:131], v[48:51]
	s_nop 1
	s_waitcnt lgkmcnt(2)
	v_lshlrev_b32_e32 v100, 16, v2
	v_mfma_f32_16x16x32_bf16 v[52:55], v[64:67], v[60:63], v[104:107]
	v_and_b32_e32 v101, 0xffff0000, v2
	s_waitcnt lgkmcnt(1)
	v_lshlrev_b32_e32 v102, 16, v192
	s_waitcnt lgkmcnt(0)
	v_lshlrev_b32_e32 v103, 16, v103
	v_mfma_f32_16x16x32_bf16 v[56:59], v[64:67], v[128:131], v[56:59]
	ds_read_b128 v[64:67], v233 offset:51008
	ds_read_u16 v116, v235 offset:1056
	ds_read_u16 v117, v235 offset:1584
	ds_read_b64 v[104:105], v234 offset:55552
	ds_read_u16 v106, v235 offset:32
	ds_read_u16 v107, v235 offset:560
	v_pk_fma_f32 v[92:93], v[154:155], v[100:101], v[92:93]
	v_pk_mul_f32 v[100:101], v[102:103], s[96:97] op_sel_hi:[1,0]
	v_lshlrev_b32_e32 v2, 16, v3
	v_exp_f32_e32 v100, v100
	v_exp_f32_e32 v101, v101
	v_and_b32_e32 v3, 0xffff0000, v3
	v_pk_fma_f32 v[2:3], v[154:155], v[2:3], v[94:95]
	v_mfma_f32_16x16x32_bf16 v[8:11], v[132:135], v[128:131], v[140:143]
	v_add_f32_e64 v100, v100, 1.0
	v_add_f32_e64 v101, v101, 1.0
	v_rcp_f32_e32 v100, v100
	v_rcp_f32_e32 v101, v101
	s_waitcnt lgkmcnt(5)
	v_mfma_f32_16x16x32_bf16 v[60:63], v[64:67], v[60:63], v[108:111]
	v_mul_f32_e64 v100, v100, v102
	v_mul_f32_e64 v101, v101, v103
	v_pk_mul_f32 v[92:93], v[92:93], v[100:101]
	v_mfma_f32_16x16x32_bf16 v[64:67], v[64:67], v[128:131], v[112:115]
	v_cvt_pk_bf16_f32 v102, v92, v93
	ds_write_b16 v235, v102
	ds_write_b16_d16_hi v235, v102 offset:528
	s_waitcnt lgkmcnt(6)
	v_lshlrev_b32_e32 v92, 16, v116
	s_waitcnt lgkmcnt(5)
	v_lshlrev_b32_e32 v93, 16, v117
	ds_read_u16 v100, v235 offset:1088
	ds_read_u16 v101, v235 offset:1616
	v_pk_mul_f32 v[94:95], v[92:93], s[96:97] op_sel_hi:[1,0]
	s_nop 0
	v_exp_f32_e32 v94, v94
	v_exp_f32_e32 v95, v95
	s_nop 0
	v_pk_add_f32 v[94:95], v[94:95], 1.0 op_sel_hi:[1,0]
	s_nop 0
	v_rcp_f32_e32 v94, v94
	v_rcp_f32_e32 v95, v95
	s_nop 0
	v_pk_mul_f32 v[92:93], v[94:95], v[92:93]
	s_nop 0
	v_pk_mul_f32 v[2:3], v[2:3], v[92:93]
	s_nop 0
	v_cvt_pk_bf16_f32 v103, v2, v3
	ds_write_b16 v235, v103 offset:1056
	ds_write_b16_d16_hi v235, v103 offset:1584
	s_waitcnt lgkmcnt(8)
	v_lshlrev_b32_e32 v92, 16, v104
	v_and_b32_e32 v93, 0xffff0000, v104
	s_waitcnt lgkmcnt(7)
	v_lshlrev_b32_e32 v94, 16, v106
	s_waitcnt lgkmcnt(6)
	v_lshlrev_b32_e32 v95, 16, v107
	v_pk_fma_f32 v[84:85], v[154:155], v[92:93], v[84:85]
	v_pk_mul_f32 v[92:93], v[94:95], s[96:97] op_sel_hi:[1,0]
	v_lshlrev_b32_e32 v2, 16, v105
	v_exp_f32_e32 v92, v92
	v_exp_f32_e32 v93, v93
	v_and_b32_e32 v3, 0xffff0000, v105
	v_pk_fma_f32 v[2:3], v[154:155], v[2:3], v[86:87]
	v_pk_add_f32 v[92:93], v[92:93], 1.0 op_sel_hi:[1,0]
	s_nop 0
	v_rcp_f32_e32 v92, v92
	v_rcp_f32_e32 v93, v93
	s_nop 0
	v_pk_mul_f32 v[92:93], v[92:93], v[94:95]
	s_nop 0
	v_pk_mul_f32 v[84:85], v[84:85], v[92:93]
	s_nop 0
	v_cvt_pk_bf16_f32 v92, v84, v85
	ds_write_b16 v235, v92 offset:32
	ds_write_b16_d16_hi v235, v92 offset:560
	s_waitcnt lgkmcnt(5)
	v_lshlrev_b32_e32 v84, 16, v100
	s_waitcnt lgkmcnt(4)
	v_lshlrev_b32_e32 v85, 16, v101
	v_pk_mul_f32 v[86:87], v[84:85], s[96:97] op_sel_hi:[1,0]
	s_nop 0
	v_exp_f32_e32 v86, v86
	v_exp_f32_e32 v87, v87
	s_nop 0
	v_pk_add_f32 v[86:87], v[86:87], 1.0 op_sel_hi:[1,0]
	s_nop 0
	v_rcp_f32_e32 v86, v86
	v_rcp_f32_e32 v87, v87
	s_nop 0
	v_pk_mul_f32 v[84:85], v[86:87], v[84:85]
	s_nop 0
	v_pk_mul_f32 v[2:3], v[2:3], v[84:85]
	v_lshlrev_b32_e32 v84, 16, v92
	v_cvt_pk_bf16_f32 v93, v2, v3
	v_and_b32_e32 v3, 64, v199
	v_xor_b32_e32 v2, 1, v199
	v_add_u32_e32 v3, 64, v3
	v_cmp_lt_i32_e32 vcc, v2, v3
	ds_write_b16 v235, v93 offset:1088
	ds_write_b16_d16_hi v235, v93 offset:1616
	v_cndmask_b32_e32 v2, v199, v2, vcc
	v_lshlrev_b32_e32 v101, 2, v2
	v_xor_b32_e32 v2, 2, v199
	v_cmp_lt_i32_e32 vcc, v2, v3
	v_and_b32_e32 v85, 0xffff0000, v92
	v_lshlrev_b32_e32 v92, 16, v93
	v_cndmask_b32_e32 v2, v199, v2, vcc
	v_lshlrev_b32_e32 v100, 2, v2
	v_xor_b32_e32 v2, 4, v199
	v_cmp_lt_i32_e32 vcc, v2, v3
	v_and_b32_e32 v93, 0xffff0000, v93
	v_pk_mul_f32 v[84:85], v[84:85], v[84:85]
	v_cndmask_b32_e32 v2, v199, v2, vcc
	v_lshlrev_b32_e32 v95, 2, v2
	v_xor_b32_e32 v2, 8, v199
	v_cmp_lt_i32_e32 vcc, v2, v3
	v_and_b32_e32 v3, 0xffff0000, v102
	v_lshlrev_b32_e32 v86, 16, v103
	v_cndmask_b32_e32 v2, v199, v2, vcc
	v_lshlrev_b32_e32 v94, 2, v2
	v_lshlrev_b32_e32 v2, 16, v102
	v_and_b32_e32 v87, 0xffff0000, v103
	v_pk_mul_f32 v[92:93], v[92:93], v[92:93]
	v_pk_fma_f32 v[2:3], v[2:3], v[2:3], v[84:85]
	v_pk_fma_f32 v[86:87], v[86:87], v[86:87], v[92:93]
	s_nop 0
	v_add_u32_e32 v102, s12, v156
	v_add_f32_dpp v2, v2, v2 quad_perm:[1,0,3,2] row_mask:0xf bank_mask:0xf
	v_add_f32_dpp v3, v3, v3 quad_perm:[1,0,3,2] row_mask:0xf bank_mask:0xf
	v_add_f32_dpp v86, v86, v86 quad_perm:[1,0,3,2] row_mask:0xf bank_mask:0xf
	v_add_f32_dpp v87, v87, v87 quad_perm:[1,0,3,2] row_mask:0xf bank_mask:0xf
	v_add_f32_dpp v2, v2, v2 quad_perm:[2,3,0,1] row_mask:0xf bank_mask:0xf
	v_add_f32_dpp v3, v3, v3 quad_perm:[2,3,0,1] row_mask:0xf bank_mask:0xf
	v_add_f32_dpp v86, v86, v86 quad_perm:[2,3,0,1] row_mask:0xf bank_mask:0xf
	v_add_f32_dpp v87, v87, v87 quad_perm:[2,3,0,1] row_mask:0xf bank_mask:0xf
	v_add_f32_dpp v2, v2, v2 row_half_mirror row_mask:0xf bank_mask:0xf
	v_add_f32_dpp v3, v3, v3 row_half_mirror row_mask:0xf bank_mask:0xf
	v_add_f32_dpp v86, v86, v86 row_half_mirror row_mask:0xf bank_mask:0xf
	v_add_f32_dpp v87, v87, v87 row_half_mirror row_mask:0xf bank_mask:0xf
	v_add_f32_dpp v84, v2, v2 row_mirror row_mask:0xf bank_mask:0xf
	v_add_f32_dpp v85, v3, v3 row_mirror row_mask:0xf bank_mask:0xf
	v_add_f32_dpp v86, v86, v86 row_mirror row_mask:0xf bank_mask:0xf
	v_add_f32_dpp v87, v87, v87 row_mirror row_mask:0xf bank_mask:0xf
	s_and_saveexec_b64 s[94:95], s[10:11]
	s_cbranch_execz .LBB0_382
	ds_write_b128 v102, v[84:87]

	.amdhsa_kernel _Z8mega_fwd4Args
		.amdhsa_group_segment_fixed_size 0
		.amdhsa_private_segment_fixed_size 0
		.amdhsa_kernarg_size 464
		.amdhsa_user_sgpr_count 2
		.amdhsa_user_sgpr_dispatch_ptr 0
		.amdhsa_user_sgpr_queue_ptr 0
		.amdhsa_user_sgpr_kernarg_segment_ptr 1
		.amdhsa_user_sgpr_dispatch_id 0
		.amdhsa_user_sgpr_kernarg_preload_length 0
		.amdhsa_user_sgpr_kernarg_preload_offset 0
		.amdhsa_user_sgpr_private_segment_size 0
		.amdhsa_uses_dynamic_stack 0
		.amdhsa_enable_private_segment 0
		.amdhsa_system_sgpr_workgroup_id_x 1
		.amdhsa_system_sgpr_workgroup_id_y 0
		.amdhsa_system_sgpr_workgroup_id_z 0
		.amdhsa_system_sgpr_workgroup_info 0
		.amdhsa_system_vgpr_workitem_id 2
		.amdhsa_next_free_vgpr 256
		.amdhsa_next_free_sgpr 102
		.amdhsa_accum_offset 256
		.amdhsa_reserve_vcc 1
		.amdhsa_float_round_mode_32 0
		.amdhsa_float_round_mode_16_64 0
		.amdhsa_float_denorm_mode_32 3
		.amdhsa_float_denorm_mode_16_64 3
		.amdhsa_dx10_clamp 1
		.amdhsa_ieee_mode 1
		.amdhsa_fp16_overflow 0
		.amdhsa_tg_split 0
		.amdhsa_exception_fp_ieee_invalid_op 0
		.amdhsa_exception_fp_denorm_src 0
		.amdhsa_exception_fp_ieee_div_zero 0
		.amdhsa_exception_fp_ieee_overflow 0
		.amdhsa_exception_fp_ieee_underflow 0
		.amdhsa_exception_fp_ieee_inexact 0
		.amdhsa_exception_int_div_zero 0
	.end_amdhsa_kernel

amdhsa.kernels:
  - .agpr_count:     0
    .args:
      - .offset:         0
        .size:           208
        .value_kind:     by_value
      - .offset:         208
        .size:           4
        .value_kind:     hidden_block_count_x
      - .offset:         212
        .size:           4
        .value_kind:     hidden_block_count_y
      - .offset:         216
        .size:           4
        .value_kind:     hidden_block_count_z
      - .offset:         220
        .size:           2
        .value_kind:     hidden_group_size_x
      - .offset:         222
        .size:           2
        .value_kind:     hidden_group_size_y
      - .offset:         224
        .size:           2
        .value_kind:     hidden_group_size_z
      - .offset:         226
        .size:           2
        .value_kind:     hidden_remainder_x
      - .offset:         228
        .size:           2
        .value_kind:     hidden_remainder_y
      - .offset:         230
        .size:           2
        .value_kind:     hidden_remainder_z
      - .offset:         248
        .size:           8
        .value_kind:     hidden_global_offset_x
      - .offset:         256
        .size:           8
        .value_kind:     hidden_global_offset_y
      - .offset:         264
        .size:           8
        .value_kind:     hidden_global_offset_z
      - .offset:         272
        .size:           2
        .value_kind:     hidden_grid_dims
      - .offset:         296
        .size:           8
        .value_kind:     hidden_multigrid_sync_arg
      - .offset:         328
        .size:           4
        .value_kind:     hidden_dynamic_lds_size
    .group_segment_fixed_size: 0
    .kernarg_segment_align: 8
    .kernarg_segment_size: 464
    .language:       OpenCL C
    .language_version:
      - 2
      - 0
    .max_flat_workgroup_size: 512
    .name:           _Z8mega_fwd4Args
    .private_segment_fixed_size: 0
    .sgpr_count:     108
    .sgpr_spill_count: 122
    .symbol:         _Z8mega_fwd4Args.kd
    .uniform_work_group_size: 1
    .uses_dynamic_stack: false
    .vgpr_count:     256
    .vgpr_spill_count: 0
    .wavefront_size: 64
